# NATTEN prologue: tile-1 K load also joins the first round (one wait for bias table, K0/V0, K1)
# speedup vs baseline: 1.0052x; 1.0027x over previous
.LBB0_1084:
	s_andn2_saveexec_b64 s[64:65], s[64:65]
	s_cbranch_execz .LBB0_1145
	v_mov_b32_e32 v33, v246
	v_mov_b32_e32 v35, v113
	v_ashrrev_i32_e32 v38, 1, v33
	v_bfe_u32 v36, v33, 5, 1
	v_bfi_b32 v2, s92, v38, v33
	v_mad_i64_i32 v[166:167], s[2:3], v2, s33, v[0:1]
	v_lshlrev_b32_e32 v34, 4, v36
	v_lshl_add_u64 v[0:1], v[166:167], 0, v[34:35]
	s_waitcnt vmcnt(0)
	global_load_dwordx4 v[114:117], v[0:1], off offset:3072
	global_load_dwordx4 v[118:121], v[0:1], off offset:3104
	global_load_dwordx4 v[122:125], v[0:1], off offset:3136
	global_load_dwordx4 v[126:129], v[0:1], off offset:3168
	v_ashrrev_i32_e32 v0, 31, v33
	v_lshrrev_b32_e32 v0, 29, v0
	v_add_u32_e32 v0, v33, v0
	v_ashrrev_i32_e32 v1, 3, v0
	v_and_b32_e32 v0, -8, v0
	v_sub_u32_e32 v174, 0, v201
	v_cmp_lt_i32_e32 vcc, 0, v201
	v_sub_u32_e32 v6, v33, v0
	v_ashrrev_i32_e32 v7, 3, v33
	v_cndmask_b32_e32 v3, v163, v141, vcc
	v_cndmask_b32_e32 v2, v162, v140, vcc
	v_cndmask_b32_e32 v9, v174, v164, vcc
	v_cndmask_b32_e32 v5, v145, v139, vcc
	v_cndmask_b32_e32 v4, v144, v138, vcc
	s_movk_i32 s6, 0x1b00
	v_and_b32_e32 v0, 7, v33
	v_mad_u64_u32 v[4:5], s[2:3], v9, s74, v[4:5]
	v_mad_i64_i32 v[168:169], s[2:3], v1, s6, 0
	v_lshlrev_b32_e32 v170, 3, v6
	v_mad_u64_u32 v[2:3], s[2:3], v9, s74, v[2:3]
	v_mad_i64_i32 v[172:173], s[2:3], v7, s6, 0
	v_lshl_add_u64 v[4:5], v[168:169], 1, v[4:5]
	v_ashrrev_i32_e32 v171, 31, v170
	v_lshl_add_u64 v[2:3], v[172:173], 1, v[2:3]
	v_lshlrev_b32_e32 v112, 4, v0
	v_lshl_add_u64 v[4:5], v[170:171], 1, v[4:5]
	v_lshl_add_u64 v[2:3], v[2:3], 0, v[112:113]
	global_load_dwordx4 v[130:133], v[4:5], off
	global_load_dwordx4 v[134:137], v[2:3], off
	v_cmp_lt_i32_e64 s[98:99], 1, v201
	s_nop 1
	v_cndmask_b32_e64 v230, v174, v164, s[98:99]
	v_add_u32_e32 v230, 1, v230
	v_cndmask_b32_e64 v233, v145, v139, s[98:99]
	v_cndmask_b32_e64 v232, v144, v138, s[98:99]
	v_mad_u64_u32 v[232:233], s[98:99], v230, s74, v[232:233]
	v_lshl_add_u64 v[232:233], v[168:169], 1, v[232:233]
	v_lshl_add_u64 v[232:233], v[170:171], 1, v[232:233]
	global_load_dwordx4 v[236:239], v[232:233], off
	s_movk_i32 s2, 0x1e0
	v_and_b32_e32 v32, 31, v33
	v_cmp_gt_i32_e32 vcc, s2, v33
	s_and_saveexec_b64 s[2:3], vcc
	s_cbranch_execz .LBB0_1090
	v_readlane_b32 s6, v254, 34
	v_cmp_ne_u32_e32 vcc, 31, v32
	s_mov_b64 s[8:9], 0
	v_lshl_add_u32 v0, v33, 2, s6
	v_mov_b32_e32 v1, v33
	s_branch .LBB0_1088

.LBB0_1090:
	s_or_b64 exec, exec, s[2:3]
	v_ashrrev_i32_e32 v0, 31, v33
	v_lshrrev_b32_e32 v0, 29, v0
	v_add_u32_e32 v0, v33, v0
	v_ashrrev_i32_e32 v1, 3, v0
	v_and_b32_e32 v0, 7, v33
	v_mul_lo_u32 v2, v7, s20
	v_add3_u32 v203, 0, v2, v112
	v_mul_lo_u32 v1, v1, s20
	v_lshlrev_b32_e32 v2, 4, v6
	v_and_b32_e32 v202, 63, v33
	v_cmp_gt_i32_e32 vcc, 1, v201
	v_add3_u32 v204, 0, v1, v2
	v_cmp_lt_i32_e64 s[6:7], 1, v142
	s_waitcnt vmcnt(0) lgkmcnt(0)
	ds_write_b128 v204, v[130:133]
	ds_write_b128 v203, v[134:137] offset:26624
	s_and_saveexec_b64 s[2:3], s[6:7]
	s_cbranch_execz .LBB0_1092
	ds_write_b128 v204, v[236:239] offset:13312
